# XCD-local barriers: affinity verdict evaluated once per half at MERGE start and kept in a VGPR lane, so the barrier leader's release path no longer does two sc1 loads
# speedup vs baseline: 1.0035x; 1.0035x over previous
; __global__ void __launch_bounds__(512, 2) fwd_mega(Args a) {
;     ...
;     unsigned char* ws = a.ws;
;     float* ada = (float*)(ws + WS_ADA); unsigned* ctl = (unsigned*)(ws + WS_CTL); float* rowss = (float*)(ws + WS_ROWSS); float* bias2 = (float*)(ws + WS_BIAS2);
;     bf16* WinT = (bf16*)(ws + WS_WIN); bf16* WattT = (bf16*)(ws + WS_WATT); bf16* WmlT = (bf16*)(ws + WS_WML); bf16* WoutT = (bf16*)(ws + WS_WOUT); bf16* Wff1T = (bf16*)(ws + WS_WFF1); bf16* Wff2T = (bf16*)(ws + WS_WFF2);
;     float* IFg = (float*)(ws + WS_IF); bf16* U = (bf16*)(ws + WS_U); bf16* P = (bf16*)(ws + WS_P); bf16* HID = (bf16*)(ws + WS_HID); bf16* OG = (bf16*)(ws + WS_OG); bf16* YPRE = (bf16*)(ws + WS_YPRE);
;     float* LSE = (float*)(ws + WS_LSE); bf16* Hb = (bf16*)(ws + WS_H); bf16* ATT = (bf16*)(ws + WS_ATT);
.LBB0_142:
	s_or_b64 exec, exec, s[0:1]
	v_readlane_b32 s12, v251, 8
	v_readlane_b32 s13, v251, 9
	s_add_u32 s0, s12, 0xc0000
	v_readlane_b32 s14, v251, 10
	v_readlane_b32 s15, v251, 11
	v_writelane_b32 v251, s0, 46
	s_addc_u32 s0, s13, 0
	v_writelane_b32 v251, s0, 47
	s_add_u32 s0, s12, 0x100000
	v_writelane_b32 v251, s0, 48
	s_addc_u32 s0, s13, 0
	v_writelane_b32 v251, s0, 49
	s_add_u32 s0, s12, 0x2c00000
	v_writelane_b32 v251, s0, 50
	s_addc_u32 s0, s13, 0
	v_writelane_b32 v251, s0, 51
	s_add_u32 s0, s12, 0x3000000
	v_writelane_b32 v251, s0, 52
	s_addc_u32 s0, s13, 0
	s_add_u32 s86, s12, 0xb000000
	s_addc_u32 s87, s13, 0
	s_add_u32 s88, s12, 0x31000000
	s_addc_u32 s89, s13, 0
	s_add_u32 s90, s12, 0x37000000
	s_addc_u32 s91, s13, 0
	s_add_u32 s16, s12, 0x37200000
	s_addc_u32 s17, s13, 0
	s_add_u32 s92, s12, 0x3b200000
	s_addc_u32 s93, s13, 0
	s_cmpk_lt_i32 s51, 0x1300
	v_writelane_b32 v251, s0, 53
	s_cselect_b64 s[0:1], -1, 0
	v_writelane_b32 v251, s0, 54
	s_ashr_i32 s94, s51, 31
	s_ashr_i32 s95, s14, 31
	v_writelane_b32 v251, s1, 55
	s_lshr_b32 s0, s94, 29
	s_add_i32 s0, s51, s0
	s_ashr_i32 s1, s0, 3
	s_and_b32 s0, s0, -8
	s_sub_i32 s0, s51, s0
	s_add_u32 s2, s12, 0x1500000
	s_addc_u32 s3, s13, 0
	v_writelane_b32 v251, s2, 56
	s_cmpk_lt_i32 s51, 0x80
	v_mov_b32_e32 v1, 0
	v_writelane_b32 v251, s3, 57
	s_cselect_b64 s[2:3], -1, 0
	v_writelane_b32 v251, s2, 58
	v_mov_b32_e32 v250, 0x2000
	v_mov_b32_e32 v189, 1
	v_writelane_b32 v251, s3, 59
	s_lshl_b32 s2, s0, 4
	s_add_u32 s4, s12, 0x1540000
	s_addc_u32 s5, s13, 0
	v_writelane_b32 v251, s4, 60
	v_mov_b32_e32 v192, 0x358637bd
	v_mov_b32_e32 v193, 0xf149f2ca
	v_writelane_b32 v251, s5, 61
	s_add_u32 s4, s12, 0x1500080
	s_addc_u32 s5, s13, 0
	v_writelane_b32 v251, s4, 62
	v_mbcnt_hi_u32_b32 v194, -1, v70
	v_mov_b32_e32 v195, 0x41b17218
	v_writelane_b32 v251, s5, 63
	s_add_u32 s4, s12, 0x1540080
	s_addc_u32 s5, s13, 0
	v_writelane_b32 v252, s4, 0
	v_mov_b64_e32 v[166:167], 0x80
	v_mov_b64_e32 v[168:169], 0x7f
	v_writelane_b32 v252, s5, 1
	s_add_u32 s4, s12, 0xc4200
	s_addc_u32 s5, s13, 0
	s_add_u32 s96, s12, 0xc4400
	s_addc_u32 s97, s13, 0
	s_add_u32 s54, s12, 0xc4500
	s_addc_u32 s55, s13, 0
	s_add_u32 s56, s12, 0xc4600
	s_addc_u32 s57, s13, 0
	s_add_u32 s58, s12, 0xc4700
	s_addc_u32 s59, s13, 0
	s_add_u32 s60, s12, 0xc4800
	s_addc_u32 s61, s13, 0
	s_add_u32 s64, s12, 0xc4900
	v_writelane_b32 v252, s4, 2
	s_addc_u32 s65, s13, 0
	v_mov_b32_e32 v240, v1
	v_writelane_b32 v252, s5, 3
	s_add_u32 s4, s12, 0xc4a00
	s_addc_u32 s5, s13, 0
	v_writelane_b32 v252, s4, 4
	v_mov_b32_e32 v241, v1
	v_mov_b32_e32 v242, v1
	v_writelane_b32 v252, s5, 5
	s_add_u32 s4, s12, 0xc4b00
	s_addc_u32 s5, s13, 0
	v_writelane_b32 v252, s4, 6
	v_mov_b32_e32 v243, v1
	v_bfrev_b32_e32 v196, 0.5
	v_writelane_b32 v252, s5, 7
	s_add_u32 s4, s12, 0xc4c00
	s_addc_u32 s5, s13, 0
	v_writelane_b32 v252, s4, 8
	v_mov_b32_e32 v197, 0x12000000
	v_mov_b64_e32 v[170:171], 0x200
	v_writelane_b32 v252, s5, 9
	s_add_u32 s4, s12, 0xc4d00
	s_addc_u32 s5, s13, 0
	v_writelane_b32 v252, s4, 10
	v_mov_b64_e32 v[172:173], 0x1ff
	v_mov_b32_e32 v198, 0x80
	v_writelane_b32 v252, s5, 11
	s_add_u32 s4, s12, 0xc4e00
	s_addc_u32 s5, s13, 0
	v_writelane_b32 v252, s4, 12
	v_mov_b64_e32 v[174:175], 0x800
	v_mov_b64_e32 v[176:177], 0x7ff
	v_writelane_b32 v252, s5, 13
	s_add_u32 s4, s12, 0xc4f00
	s_addc_u32 s5, s13, 0
	v_writelane_b32 v252, s4, 14
	s_mov_b64 s[84:85], 0x80
	s_waitcnt lgkmcnt(0)
	v_writelane_b32 v252, s5, 15
	s_add_u32 s4, s12, 0xc5000
	s_addc_u32 s5, s13, 0
	v_writelane_b32 v252, s4, 16
	s_barrier
	s_nop 0
	v_writelane_b32 v252, s5, 17
	s_add_u32 s4, s12, 0xc5100
	s_addc_u32 s5, s13, 0
	v_writelane_b32 v252, s4, 18
	s_nop 1
	v_writelane_b32 v252, s5, 19
	s_add_u32 s4, s12, 0xc5200
	s_addc_u32 s5, s13, 0
	v_writelane_b32 v252, s4, 20
	s_nop 1
	v_writelane_b32 v252, s5, 21
	s_add_u32 s4, s12, 0xc5300
	s_addc_u32 s5, s13, 0
	v_writelane_b32 v252, s4, 22
	s_nop 1
	v_writelane_b32 v252, s5, 23
	s_add_u32 s4, s12, 0xc7400
	s_addc_u32 s5, s13, 0
	v_writelane_b32 v252, s4, 24
	s_nop 1
	v_writelane_b32 v252, s5, 25
	s_add_u32 s4, s12, 0xc7500
	s_addc_u32 s5, s13, 0
	s_lshl_b32 s3, s51, 9
	s_add_u32 s30, s12, 0x33000000
	s_addc_u32 s31, s13, 0
	s_add_u32 s48, s12, 0x35000000
	v_writelane_b32 v252, s4, 26
	s_addc_u32 s49, s13, 0
	s_lshl_b32 s50, s14, 9
	v_writelane_b32 v252, s5, 27
	s_cmpk_lt_i32 s51, 0x200
	v_writelane_b32 v252, s3, 28
	s_cselect_b64 s[4:5], -1, 0
	s_lshl_b32 s3, s0, 6
	v_writelane_b32 v252, s4, 29
	s_cmpk_lt_i32 s51, 0x800
	s_nop 0
	v_writelane_b32 v252, s5, 30
	s_cselect_b64 s[4:5], -1, 0
	v_writelane_b32 v252, s4, 31
	s_nop 1
	v_writelane_b32 v252, s5, 32
	s_lshl_b32 s4, s0, 8
	s_add_u32 s5, s12, 0x5000
	v_writelane_b32 v252, s5, 33
	s_addc_u32 s5, s13, 0
	v_writelane_b32 v252, s5, 34
	s_cmp_lt_i32 s0, 0
	s_mul_i32 s5, s0, 17
	s_cselect_b32 s2, s5, s2
	s_mul_i32 s5, s0, 0x41
	s_cselect_b32 s3, s5, s3
	s_movk_i32 s5, 0x261
	s_cselect_b32 s5, s5, 0x260
	s_mul_i32 s5, s0, s5
	s_mulk_i32 s0, 0x101
	s_cselect_b32 s8, s0, s4
	s_add_i32 s5, s5, s1
	s_mul_hi_i32 s0, s5, 0x6bca1af3
	s_lshr_b32 s4, s0, 31
	s_ashr_i32 s0, s0, 7
	s_add_i32 s0, s0, s4
	s_mul_i32 s4, s0, 0x130
	s_sub_i32 s4, s5, s4
	s_bfe_u32 s5, s4, 0x3001c
	s_add_i32 s5, s4, s5
	s_and_b32 s6, s5, 0xfff8
	s_add_i32 s3, s3, s1
	s_sub_i32 s4, s4, s6
	s_ashr_i32 s6, s3, 31
	s_lshr_b32 s6, s6, 27
	s_add_i32 s6, s3, s6
	s_and_b32 s7, s6, 0xffe0
	s_sub_i32 s3, s3, s7
	s_bfe_i32 s7, s3, 0x80000
	s_bfe_u32 s7, s7, 0x3000c
	s_add_i32 s7, s3, s7
	s_and_b32 s9, s7, 0xf8
	s_lshl_b32 s0, s0, 3
	s_sext_i32_i16 s4, s4
	s_sub_i32 s3, s3, s9
	s_add_i32 s12, s0, s4
	s_add_i32 s10, s2, s1
;     __host__ __device__ bool next(int i, Unit& u) const {
;         const long L = (long)i * G + c; if (L >= nwg) return false;
;         int wgid = (int)L; { const int q = nwg / NXCD, r = nwg % NXCD, xcd = wgid % NXCD, off = wgid / NXCD; wgid = (xcd < r ? xcd * (q + 1) : r * (q + 1) + (xcd - r) * q) + off; }
;         const int nig = WGM * nN, gid = wgid / nig, fm = gid * WGM, gsz = (nM - fm) < WGM ? (nM - fm) : WGM;
;         u.pm = fm + ((wgid % nig) % gsz); u.pn = (wgid % nig) / gsz; return true;
;     }
; template <class Epi, class Sched, bool ALIGN_EPI = false, bool SP2 = false>
; __device__ __forceinline__ void gemm_phase(PG8_LAS unsigned char* lds, const Gemm g, const Sched& S, const Epi& E) {
;     ...
;     const char* cA = (const char*)g.A + (size_t)cur.pm * tstep; const char* cB = (const char*)g.Bt + (size_t)cur.pn * tstep;
	s_ashr_i32 s0, s6, 5
	s_bfe_i32 s2, s7, 0x80000
	s_lshl_b32 s0, s0, 3
	s_sext_i32_i16 s2, s2
	s_sext_i32_i8 s3, s3
	s_add_i32 s18, s0, s3
	s_ashr_i32 s0, s2, 3
	s_sext_i32_i16 s5, s5
	v_writelane_b32 v252, s0, 35
	s_lshr_b32 s0, s2, 3
	s_bfe_i64 s[6:7], s[0:1], 0x100000
	s_ashr_i32 s0, s5, 3
	v_writelane_b32 v252, s0, 36
	s_mov_b32 s2, s10
	s_ashr_i32 s11, s10, 31
	v_writelane_b32 v252, s2, 37
	s_ashr_i32 s19, s18, 31
	s_lshr_b32 s0, s5, 3
	v_writelane_b32 v252, s3, 38
	s_lshl_b64 s[2:3], s[10:11], 19
	v_writelane_b32 v252, s2, 39
	s_lshl_b64 s[4:5], s[6:7], 18
	v_readlane_b32 s10, v251, 34
	v_writelane_b32 v252, s3, 40
	s_lshl_b64 s[2:3], s[18:19], 18
	v_readlane_b32 s11, v251, 35
	s_add_u32 s4, s10, s4
	s_addc_u32 s5, s11, s5
	s_add_u32 s10, s4, 0x20000
	s_addc_u32 s11, s5, 0
	v_writelane_b32 v252, s10, 41
	s_add_u32 s2, s92, s2
	s_addc_u32 s3, s93, s3
	v_writelane_b32 v252, s11, 42
	s_add_u32 s10, s2, 0x20000
	v_writelane_b32 v252, s2, 43
	s_addc_u32 s11, s3, 0
	s_nop 0
	v_writelane_b32 v252, s3, 44
	v_writelane_b32 v252, s10, 45
	s_add_u32 s2, s4, 0x20080
	s_nop 0
	v_writelane_b32 v252, s11, 46
	v_writelane_b32 v252, s4, 47
	s_addc_u32 s3, s5, 0
	v_readlane_b32 s10, v251, 36
	v_writelane_b32 v252, s5, 48
	v_writelane_b32 v252, s2, 49
	s_lshl_b64 s[4:5], s[6:7], 19
	v_readlane_b32 s11, v251, 37
	v_writelane_b32 v252, s3, 50
	s_lshl_b64 s[2:3], s[18:19], 19
	s_add_u32 s10, s10, s4
	s_addc_u32 s11, s11, s5
	s_add_u32 s20, s10, 0x40000
	s_addc_u32 s21, s11, 0
	v_writelane_b32 v252, s20, 51
	s_nop 1
	v_writelane_b32 v252, s21, 52
	v_writelane_b32 v252, s16, 53
	s_add_u32 s16, s16, s2
	v_writelane_b32 v252, s17, 54
	s_addc_u32 s17, s17, s3
	s_add_u32 s20, s16, 0x40000
	v_writelane_b32 v252, s16, 55
	s_addc_u32 s21, s17, 0
	s_nop 0
	v_writelane_b32 v252, s17, 56
	v_writelane_b32 v252, s20, 57
	s_add_u32 s16, s10, 0x40080
	s_nop 0
	v_writelane_b32 v252, s21, 58
	v_writelane_b32 v252, s10, 59
	s_addc_u32 s17, s11, 0
	s_add_i32 s1, s8, s1
	s_ashr_i32 s8, s1, 31
	s_lshr_b32 s8, s8, 25
	s_add_i32 s8, s1, s8
	s_and_b32 s9, s8, 0xff80
	s_sub_i32 s1, s1, s9
	s_bfe_i32 s9, s1, 0x80000
	s_bfe_u32 s9, s9, 0x3000c
	s_add_i32 s9, s1, s9
	v_writelane_b32 v252, s11, 60
	s_and_b32 s10, s9, 0xf8
	s_sub_i32 s1, s1, s10
	s_ashr_i32 s8, s8, 7
	v_writelane_b32 v252, s16, 61
	s_lshl_b32 s8, s8, 3
	s_sext_i32_i8 s1, s1
	v_writelane_b32 v252, s17, 62
	s_add_i32 s16, s8, s1
	s_bfe_i32 s9, s9, 0x80000
	s_mov_b32 s10, s16
	s_sext_i32_i16 s9, s9
	s_ashr_i32 s17, s16, 31
	v_writelane_b32 v253, s10, 0
	s_lshr_b32 s8, s9, 3
	s_ashr_i32 s1, s9, 3
	v_writelane_b32 v253, s11, 1
	s_lshl_b64 s[10:11], s[16:17], 19
	s_bfe_i64 s[8:9], s[8:9], 0x100000
	v_writelane_b32 v253, s10, 2
	s_lshl_b64 s[8:9], s[8:9], 19
	v_writelane_b32 v252, s1, 63
	v_writelane_b32 v253, s11, 3
	v_readlane_b32 s10, v251, 40
	v_readlane_b32 s11, v251, 41
	s_add_u32 s8, s10, s8
	s_addc_u32 s9, s11, s9
	s_add_u32 s10, s8, 0x40000
	s_addc_u32 s11, s9, 0
	v_writelane_b32 v253, s10, 4
	s_nop 1
	v_writelane_b32 v253, s11, 5
	s_add_u32 s10, s8, 0x40080
	v_writelane_b32 v253, s8, 6
	s_addc_u32 s11, s9, 0
	s_lshl_b64 s[6:7], s[6:7], 21
	v_writelane_b32 v253, s9, 7
	v_writelane_b32 v253, s10, 8
	s_mov_b32 s8, s18
	s_nop 0
	v_writelane_b32 v253, s11, 9
	v_writelane_b32 v253, s8, 10
	v_readlane_b32 s10, v251, 42
	v_readlane_b32 s11, v251, 43
	v_writelane_b32 v253, s9, 11
	s_lshl_b64 s[8:9], s[18:19], 21
	s_add_u32 s6, s10, s6
	s_addc_u32 s7, s11, s7
	s_add_u32 s10, s6, 0x100000
	s_addc_u32 s11, s7, 0
	v_writelane_b32 v253, s10, 12
	s_add_u32 s8, s86, s8
	s_addc_u32 s9, s87, s9
	v_writelane_b32 v253, s11, 13
	s_add_u32 s10, s8, 0x100000
	v_writelane_b32 v253, s8, 14
	s_addc_u32 s11, s9, 0
	s_nop 0
	v_writelane_b32 v253, s9, 15
	v_writelane_b32 v253, s10, 16
	s_add_u32 s8, s6, 0x100080
	s_nop 0
	v_writelane_b32 v253, s11, 17
	v_writelane_b32 v253, s6, 18
	s_addc_u32 s9, s7, 0
	s_ashr_i32 s13, s12, 31
	v_writelane_b32 v253, s7, 19
	v_writelane_b32 v253, s8, 20
	s_mov_b32 s6, s12
	s_bfe_i64 s[0:1], s[0:1], 0x100000
	v_writelane_b32 v253, s9, 21
	v_writelane_b32 v253, s6, 22
	s_lshl_b64 s[0:1], s[0:1], 19
	s_mov_b64 s[10:11], s[62:63]
	v_writelane_b32 v253, s7, 23
	s_lshl_b64 s[6:7], s[12:13], 19
	v_writelane_b32 v253, s6, 24
	s_nop 1
	v_writelane_b32 v253, s7, 25
	v_readlane_b32 s6, v251, 32
	v_readlane_b32 s7, v251, 33
	s_add_u32 s0, s6, s0
	s_addc_u32 s1, s7, s1
	s_add_u32 s6, s0, 0x40000
	s_addc_u32 s7, s1, 0
	v_writelane_b32 v253, s6, 26
	s_nop 1
	v_writelane_b32 v253, s7, 27
; #define LAS __attribute__((address_space(3)))
; __global__ void __launch_bounds__(512, 2) fwd_mega(Args a) {
;     ...
;     volatile LAS unsigned* bst = (volatile LAS unsigned*)(lds + LDS_BYTES - 16);
;     if (threadIdx.x == 0) { bst[0] = 0u; bst[1] = 0u; }
;     __syncthreads();
;     (void)xcd_barrier_post(ctl + 4096, bst);
	s_add_u32 s6, s0, 0x40080
	v_writelane_b32 v253, s0, 28
	s_addc_u32 s7, s1, 0
	s_nop 0
	v_writelane_b32 v253, s1, 29
	v_readlane_b32 s0, v251, 38
	v_readlane_b32 s1, v251, 39
	s_add_u32 s4, s0, s4
	s_addc_u32 s5, s1, s5
	v_writelane_b32 v253, s6, 30
	s_add_u32 s0, s4, 0x40000
	s_addc_u32 s1, s5, 0
	v_writelane_b32 v253, s7, 31
	v_writelane_b32 v253, s0, 32
	s_add_u32 s2, s88, s2
	s_addc_u32 s3, s89, s3
	v_writelane_b32 v253, s1, 33
	s_mul_i32 s0, s15, s14
	s_mul_i32 s0, s0, s33
	v_writelane_b32 v253, s0, 34
	s_add_u32 s0, s2, 0x40000
	v_writelane_b32 v253, s2, 35
	s_addc_u32 s1, s3, 0
	s_nop 0
	v_writelane_b32 v253, s3, 36
	v_writelane_b32 v253, s0, 37
	s_mov_b32 s2, 0
	s_nop 0
	v_writelane_b32 v253, s1, 38
	s_add_u32 s0, s4, 0x40080
	v_writelane_b32 v253, s4, 39
	s_addc_u32 s1, s5, 0
	s_bitcmp1_b32 s51, 0
	v_writelane_b32 v253, s5, 40
	v_writelane_b32 v253, s0, 41
	s_nop 1
	v_writelane_b32 v253, s1, 42
	s_cselect_b64 s[0:1], -1, 0
	v_writelane_b32 v253, s0, 43
	s_bitcmp1_b32 s14, 0
	s_nop 0
	v_writelane_b32 v253, s1, 44
	s_mov_b32 s0, s14
	v_writelane_b32 v253, s0, 45
	s_cselect_b64 s[0:1], -1, 0
	v_writelane_b32 v253, s0, 46
	s_nop 1
	v_writelane_b32 v253, s1, 47
	s_lshl_b32 s0, s51, 12
	v_writelane_b32 v253, s0, 48
	s_lshl_b32 s0, s14, 12
	v_writelane_b32 v253, s0, 49
	s_add_i32 s0, 0, 0x23ff0
	v_writelane_b32 v253, s0, 50
	s_add_i32 s0, 0, 0x23ff4
	v_writelane_b32 v253, s0, 51
	s_add_i32 s0, 0, 0xc800
	v_writelane_b32 v253, s0, 52
	s_add_i32 s0, 0, 0x13300
	v_writelane_b32 v253, s0, 53
	s_add_i32 s0, 0, 0x12b00
	v_writelane_b32 v253, s0, 54
	s_add_i32 s0, 0, 0x11d00
	v_writelane_b32 v253, s0, 55
	s_add_i32 s0, 0, 0x12600
	v_writelane_b32 v253, s0, 56
	s_add_i32 s0, 0, 0x11e00
	v_writelane_b32 v253, s0, 57
	s_add_i32 s0, 0, 0x11c00
	v_writelane_b32 v253, s0, 58
	s_add_i32 s0, 0, 0x11c20
	v_writelane_b32 v253, s0, 59
	s_add_i32 s0, 0, 0x11c40
	v_writelane_b32 v253, s0, 60
	s_add_i32 s0, 0, 0x11c60
	v_writelane_b32 v253, s0, 61
	s_add_i32 s0, 0, 0x11c80
	v_writelane_b32 v253, s0, 62
	s_add_i32 s0, 0, 0x11ca0
	v_writelane_b32 v253, s0, 63
	s_add_i32 s0, 0, 0x11cc0
	v_writelane_b32 v254, s0, 0
	s_add_i32 s0, 0, 0x11ce0
	v_writelane_b32 v254, s0, 1
	s_add_i32 s0, 0, 0x13600
	v_writelane_b32 v254, s0, 2
	s_add_i32 s0, 0, 0x9694
	v_writelane_b32 v254, s0, 3
	s_mov_b64 s[0:1], -1
	v_writelane_b32 v254, s0, 4
	s_mov_b64 s[14:15], s[66:67]
	s_nop 0
	v_writelane_b32 v254, s1, 5
	s_mov_b32 s1, 0
	v_writelane_b32 v254, s0, 6
	s_nop 1
	v_writelane_b32 v254, s1, 7
	s_mov_b64 s[0:1], s[52:53]
	v_writelane_b32 v254, s0, 8
	s_nop 1
	v_writelane_b32 v254, s1, 9
	v_writelane_b32 v254, s2, 10
	v_writelane_b32 v254, s3, 11
	v_writelane_b32 v254, s4, 12
	v_writelane_b32 v254, s5, 13
	v_writelane_b32 v254, s6, 14
	v_writelane_b32 v254, s7, 15
	v_writelane_b32 v254, s8, 16
	v_writelane_b32 v254, s9, 17
	v_writelane_b32 v254, s10, 18
	v_writelane_b32 v254, s11, 19
	v_writelane_b32 v254, s12, 20
	v_writelane_b32 v254, s13, 21
	v_writelane_b32 v254, s14, 22
	v_writelane_b32 v254, s15, 23
	v_writelane_b32 v254, s54, 24
	s_nop 1
	v_writelane_b32 v254, s55, 25
	v_writelane_b32 v254, s56, 26
	s_nop 1
	v_writelane_b32 v254, s57, 27
	v_writelane_b32 v254, s58, 28
	s_nop 1
	v_writelane_b32 v254, s59, 29
	v_writelane_b32 v254, s60, 30
	s_nop 1
	v_writelane_b32 v254, s61, 31
	v_writelane_b32 v254, s64, 32
	s_nop 1
	v_writelane_b32 v254, s65, 33
	v_writelane_b32 v254, s30, 34
	s_nop 1
	v_writelane_b32 v254, s31, 35
	v_writelane_b32 v254, s48, 36
	s_nop 1
	v_writelane_b32 v254, s49, 37
	v_writelane_b32 v254, s50, 38
	v_writelane_b32 v254, s51, 39
	v_writelane_b32 v254, s86, 40
	s_nop 1
	v_writelane_b32 v254, s87, 41
	v_writelane_b32 v254, s88, 42
	s_nop 1
	v_writelane_b32 v254, s89, 43
	v_writelane_b32 v254, s90, 44
	s_nop 1
	v_writelane_b32 v254, s91, 45
	v_writelane_b32 v254, s92, 46
	s_nop 1
	v_writelane_b32 v254, s93, 47
	v_writelane_b32 v254, s94, 48
	v_writelane_b32 v254, s95, 49
	v_writelane_b32 v254, s96, 50
	s_nop 1
	v_writelane_b32 v254, s97, 51
	s_getreg_b32 s98, hwreg(HW_REG_XCC_ID, 0, 4)
	s_lshl_b32 s98, 1, s98
	v_mov_b32_e32 v0, s98
	s_and_b32 s99, s51, 7
	s_lshl_b32 s99, s99, 2
	v_readlane_b32 s100, v252, 26
	v_readlane_b32 s101, v252, 27
	s_add_u32 s100, s100, s99
	s_addc_u32 s101, s101, 0
	v_cmp_eq_u32_e32 vcc, 0, v188
	s_and_saveexec_b64 s[98:99], vcc
	s_nop 3
	global_atomic_or v1, v0, s[100:101] offset:32
	s_or_b64 exec, exec, s[98:99]
	v_writelane_b32 v255, 0, 48
	v_writelane_b32 v255, 0, 49
	s_branch .LBB0_146

; #define FRESH_IDS() int tid = threadIdx.x; asm volatile("" : "+v"(tid)); const int lane = tid & 63, wave = __builtin_amdgcn_readfirstlane(tid >> 6), gw = bx * 8 + wave; (void)lane; (void)gw
; #define GBAR() do { XcdBarrier xb_; xb_.bar = (unsigned*)(a.ws + WS_CTL) + 4096; xb_.x = xb_xcc_id(); xb_.st = (volatile LAS unsigned*)(lds + LDS_BYTES - 16); xcd_barrier(xb_); } while (0)
; __global__ void __launch_bounds__(512, 2) fwd_mega(Args a) {
;     ...
;         GBAR();
;         { FRESH_IDS();
;         for (int i = bx * 512 + tid; i < TH * 64; i += G * 512) {
;             const int tok = i >> 6, rem = i & 63, hs = rem >> 4, ch = rem & 15;
.LBB0_491:
	s_or_b64 exec, exec, s[0:1]
	s_waitcnt lgkmcnt(0)
	v_mov_b32_e32 v2, v188
	v_readlane_b32 s0, v252, 28
	s_barrier
	v_readlane_b32 s100, v252, 26
	v_readlane_b32 s101, v252, 27
	s_nop 4
	global_load_dwordx4 v[4:7], v1, s[100:101] offset:32 sc1
	global_load_dwordx4 v[8:11], v1, s[100:101] offset:48 sc1
	s_waitcnt vmcnt(0)
	v_add_u32_e32 v12, -1, v4
	v_and_b32_e32 v12, v12, v4
	v_min_u32_e32 v13, v4, v5
	v_add_u32_e32 v14, -1, v5
	v_and_or_b32 v12, v14, v5, v12
	v_min_u32_e32 v13, v13, v5
	v_add_u32_e32 v14, -1, v6
	v_and_or_b32 v12, v14, v6, v12
	v_min_u32_e32 v13, v13, v6
	v_add_u32_e32 v14, -1, v7
	v_and_or_b32 v12, v14, v7, v12
	v_min_u32_e32 v13, v13, v7
	v_add_u32_e32 v14, -1, v8
	v_and_or_b32 v12, v14, v8, v12
	v_min_u32_e32 v13, v13, v8
	v_add_u32_e32 v14, -1, v9
	v_and_or_b32 v12, v14, v9, v12
	v_min_u32_e32 v13, v13, v9
	v_add_u32_e32 v14, -1, v10
	v_and_or_b32 v12, v14, v10, v12
	v_min_u32_e32 v13, v13, v10
	v_add_u32_e32 v14, -1, v11
	v_and_or_b32 v12, v14, v11, v12
	v_min_u32_e32 v13, v13, v11
	v_cmp_eq_u32_e32 vcc, 0, v13
	s_nop 1
	v_cndmask_b32_e64 v13, 0, 1, vcc
	v_or_b32_e32 v12, v12, v13
	s_nop 0
	v_readfirstlane_b32 s98, v12
	s_cmp_eq_u32 s98, 0
	s_cselect_b32 s98, 1, 2
	s_nop 0
	v_writelane_b32 v255, s98, 49
	s_nop 0
	v_add_u32_e32 v0, s0, v2
	s_mov_b32 s0, 0x200000
	v_cmp_gt_i32_e32 vcc, s0, v0
	s_and_saveexec_b64 s[0:1], vcc
	v_readlane_b32 s6, v253, 49
	s_cbranch_execz .LBB0_494
	v_readlane_b32 s2, v253, 48
	s_nop 1
	v_lshl_add_u32 v2, v2, 3, s2
	s_mov_b64 s[2:3], 0

; __device__ __forceinline__ unsigned xb_ld(unsigned* p)              { return __hip_atomic_load(p, __ATOMIC_RELAXED, __HIP_MEMORY_SCOPE_AGENT); }
; __device__ __forceinline__ unsigned xb_add(unsigned* p, unsigned v) { return __hip_atomic_fetch_add(p, v, __ATOMIC_RELAXED, __HIP_MEMORY_SCOPE_AGENT); }
; #define XB_SPIN(cond, bar) do { unsigned _sp = 0; while (cond) { __builtin_amdgcn_s_sleep(1); \
;     if ((++_sp & 255u) == 0u) { if (xb_ld(&(bar)[XB_TMO])) break; if (_sp > XB_SPIN_CAP) { atomicAdd(&(bar)[XB_TMO], 1u); break; } } } } while (0)
; __device__ __forceinline__ void xcd_barrier(const XcdBarrier& b) {
;     ...
;         const unsigned old = xb_add(&bar[XB_XSUB(b.x)], 1u);
;         const unsigned gen = old / nloc;
;         if (old + 1u == (gen + 1u) * nloc) {
;             __builtin_amdgcn_fence(__ATOMIC_RELEASE, "agent");
;             asm volatile("s_waitcnt vmcnt(0)" ::: "memory");
;             const unsigned og = xb_add(&bar[XB_TOP], 1u);
;             const unsigned tg = og / nx;
;             if (og + 1u == (tg + 1u) * nx) xb_add(&bar[XB_TOPGEN], 1u);
;             else XB_SPIN(xb_ld(&bar[XB_TOPGEN]) == tg, bar);
;             __builtin_amdgcn_fence(__ATOMIC_ACQUIRE, "agent");
;             xb_add(&bar[XB_XGEN(b.x)], 1u);
;             asm volatile("s_waitcnt vmcnt(0)" ::: "memory");
;         } else {
;             XB_SPIN(xb_ld(&bar[XB_XGEN(b.x)]) == gen, bar);
.LBB0_618:
	s_andn2_saveexec_b64 s[6:7], s[6:7]
	s_cbranch_execz .LBB0_638
	s_mov_b64 s[6:7], exec
	buffer_wbl2 sc1
	s_waitcnt lgkmcnt(0)
	s_waitcnt vmcnt(0)
	v_readlane_b32 s98, v255, 49
	s_nop 0
	s_cmp_eq_u32 s98, 1
	s_cbranch_scc1 .LBB0_635
	v_mbcnt_lo_u32_b32 v0, s6, 0
	v_mbcnt_hi_u32_b32 v0, s7, v0
	v_cmp_eq_u32_e32 vcc, 0, v0
	s_and_saveexec_b64 s[8:9], vcc
	s_cbranch_execz .LBB0_621
	s_bcnt1_i32_b64 s6, s[6:7]
	v_mov_b32_e32 v3, s6
	v_readlane_b32 s6, v252, 24
	v_readlane_b32 s7, v252, 25
	s_nop 4
	global_atomic_add v3, v1, v3, s[6:7] sc0

; __device__ __forceinline__ unsigned xb_ld(unsigned* p)              { return __hip_atomic_load(p, __ATOMIC_RELAXED, __HIP_MEMORY_SCOPE_AGENT); }
; __device__ __forceinline__ unsigned xb_add(unsigned* p, unsigned v) { return __hip_atomic_fetch_add(p, v, __ATOMIC_RELAXED, __HIP_MEMORY_SCOPE_AGENT); }
; #define XB_SPIN(cond, bar) do { unsigned _sp = 0; while (cond) { __builtin_amdgcn_s_sleep(1); \
;     if ((++_sp & 255u) == 0u) { if (xb_ld(&(bar)[XB_TMO])) break; if (_sp > XB_SPIN_CAP) { atomicAdd(&(bar)[XB_TMO], 1u); break; } } } } while (0)
; __device__ __forceinline__ void xcd_barrier(const XcdBarrier& b) {
;     ...
;         const unsigned old = xb_add(&bar[XB_XSUB(b.x)], 1u);
;         const unsigned gen = old / nloc;
;         if (old + 1u == (gen + 1u) * nloc) {
;             __builtin_amdgcn_fence(__ATOMIC_RELEASE, "agent");
;             asm volatile("s_waitcnt vmcnt(0)" ::: "memory");
;             const unsigned og = xb_add(&bar[XB_TOP], 1u);
;             const unsigned tg = og / nx;
;             if (og + 1u == (tg + 1u) * nx) xb_add(&bar[XB_TOPGEN], 1u);
;             else XB_SPIN(xb_ld(&bar[XB_TOPGEN]) == tg, bar);
;             __builtin_amdgcn_fence(__ATOMIC_ACQUIRE, "agent");
;             xb_add(&bar[XB_XGEN(b.x)], 1u);
;             asm volatile("s_waitcnt vmcnt(0)" ::: "memory");
;         } else {
;             XB_SPIN(xb_ld(&bar[XB_XGEN(b.x)]) == gen, bar);
.LBB0_706:
	s_andn2_saveexec_b64 s[6:7], s[6:7]
	s_cbranch_execz .LBB0_726
	s_mov_b64 s[6:7], exec
	buffer_wbl2 sc1
	s_waitcnt lgkmcnt(0)
	s_waitcnt vmcnt(0)
	v_readlane_b32 s98, v255, 49
	s_nop 0
	s_cmp_eq_u32 s98, 1
	s_cbranch_scc1 .LBB0_723
	v_mbcnt_lo_u32_b32 v0, s6, 0
	v_mbcnt_hi_u32_b32 v0, s7, v0
	v_cmp_eq_u32_e32 vcc, 0, v0
	s_and_saveexec_b64 s[14:15], vcc
	s_cbranch_execz .LBB0_709
	s_bcnt1_i32_b64 s6, s[6:7]
	v_mov_b32_e32 v3, s6
	v_readlane_b32 s6, v252, 24
	v_readlane_b32 s7, v252, 25
	s_nop 4
	global_atomic_add v3, v1, v3, s[6:7] sc0

; __device__ __forceinline__ unsigned xb_ld(unsigned* p)              { return __hip_atomic_load(p, __ATOMIC_RELAXED, __HIP_MEMORY_SCOPE_AGENT); }
; __device__ __forceinline__ unsigned xb_add(unsigned* p, unsigned v) { return __hip_atomic_fetch_add(p, v, __ATOMIC_RELAXED, __HIP_MEMORY_SCOPE_AGENT); }
; #define XB_SPIN(cond, bar) do { unsigned _sp = 0; while (cond) { __builtin_amdgcn_s_sleep(1); \
;     if ((++_sp & 255u) == 0u) { if (xb_ld(&(bar)[XB_TMO])) break; if (_sp > XB_SPIN_CAP) { atomicAdd(&(bar)[XB_TMO], 1u); break; } } } } while (0)
; __device__ __forceinline__ void xcd_barrier(const XcdBarrier& b) {
;     ...
;         const unsigned old = xb_add(&bar[XB_XSUB(b.x)], 1u);
;         const unsigned gen = old / nloc;
;         if (old + 1u == (gen + 1u) * nloc) {
;             __builtin_amdgcn_fence(__ATOMIC_RELEASE, "agent");
;             asm volatile("s_waitcnt vmcnt(0)" ::: "memory");
;             const unsigned og = xb_add(&bar[XB_TOP], 1u);
;             const unsigned tg = og / nx;
;             if (og + 1u == (tg + 1u) * nx) xb_add(&bar[XB_TOPGEN], 1u);
;             else XB_SPIN(xb_ld(&bar[XB_TOPGEN]) == tg, bar);
;             __builtin_amdgcn_fence(__ATOMIC_ACQUIRE, "agent");
;             xb_add(&bar[XB_XGEN(b.x)], 1u);
;             asm volatile("s_waitcnt vmcnt(0)" ::: "memory");
;         } else {
;             XB_SPIN(xb_ld(&bar[XB_XGEN(b.x)]) == gen, bar);
.LBB0_778:
	s_andn2_saveexec_b64 s[6:7], s[6:7]
	s_cbranch_execz .LBB0_798
	s_mov_b64 s[10:11], exec
	buffer_wbl2 sc1
	s_waitcnt lgkmcnt(0)
	s_waitcnt vmcnt(0)
	v_readlane_b32 s98, v255, 49
	s_nop 0
	s_cmp_eq_u32 s98, 1
	s_cbranch_scc1 .LBB0_795
	v_mbcnt_lo_u32_b32 v0, s10, 0
	v_mbcnt_hi_u32_b32 v0, s11, v0
	v_cmp_eq_u32_e32 vcc, 0, v0
	s_and_saveexec_b64 s[12:13], vcc
	s_cbranch_execz .LBB0_781
	s_bcnt1_i32_b64 s10, s[10:11]
	v_mov_b32_e32 v3, s10
	v_readlane_b32 s10, v252, 24
	v_readlane_b32 s11, v252, 25
	s_nop 4
	global_atomic_add v3, v1, v3, s[10:11] sc0
